# scan-v10-tw-pload-buffer-form
# baseline (speedup 1.0000x reference)
.LBB0_539:
	s_and_b32 s61, s23, 0xffff
	s_add_u32 s40, s22, 0x1000000
	s_addc_u32 s41, s23, 0
	s_and_b64 s[18:19], s[16:17], exec
	s_cselect_b32 s18, 0x780, 64
	s_lshl_b32 s19, s18, 10
	buffer_load_dwordx4 v[62:65], v1, s[52:55], s19 offen
	buffer_load_dwordx4 v[58:61], v203, s[52:55], s19 offen
	buffer_load_dwordx4 v[54:57], v204, s[52:55], s19 offen
	buffer_load_dwordx4 v[50:53], v205, s[52:55], s19 offen
	buffer_load_dwordx4 v[46:49], v206, s[52:55], s19 offen
	buffer_load_dwordx4 v[42:45], v207, s[52:55], s19 offen
	s_lshl_b32 s18, s18, 5
	buffer_load_dwordx4 v[38:41], v208, s[52:55], s19 offen
	buffer_load_dword v212, v209, s[56:59], s18 offen
	s_lshl_b32 s18, s95, 6
	s_lshl_b32 s2, s2, 15
	s_mov_b32 s60, s22
	s_xor_b32 s22, s18, 0x2000
	s_sub_i32 s50, s66, s2
	s_lshl_b32 s0, s0, 2
	s_ashr_i32 s23, s22, 31
	s_add_i32 s50, s50, 0x8000
	s_or_b32 s27, s0, 0xe00000
	s_and_b64 s[24:25], s[16:17], exec
	s_cselect_b32 s0, 0x200, 0
	s_add_i32 s0, s0, 0
	s_and_b64 s[24:25], s[16:17], exec
	s_cselect_b32 s19, 0, 0x200
	s_add_i32 s28, s19, 0
	s_or_b32 s29, s2, s66
	s_ashr_i32 s19, s18, 31
	s_lshl_b64 s[22:23], s[22:23], 2
	s_add_u32 s42, s93, s22
	s_addc_u32 s43, s94, s23
	s_lshl_b64 s[18:19], s[18:19], 2
	s_add_u32 s44, s93, s18
	s_addc_u32 s45, s94, s19
	s_lshl_b32 s2, s1, 1
	s_waitcnt vmcnt(12)
	v_lshlrev_b32_e32 v2, 2, v150
	s_add_u32 s46, s40, s2
	v_mov_b32_e32 v22, 0
	s_mov_b32 s51, 0
	v_add_u32_e32 v210, s0, v2
	v_add_u32_e32 v211, s28, v2
	s_addc_u32 s47, s41, 0
	v_mov_b32_e32 v23, v22
	v_mov_b32_e32 v24, v22
	v_mov_b32_e32 v25, v22
	v_mov_b32_e32 v26, v22
	v_mov_b32_e32 v27, v22
	v_mov_b32_e32 v28, v22
	v_mov_b32_e32 v29, v22
	v_mov_b32_e32 v30, v22
	v_mov_b32_e32 v31, v22
	v_mov_b32_e32 v32, v22
	v_mov_b32_e32 v33, v22
	v_mov_b32_e32 v34, v22
	v_mov_b32_e32 v35, v22
	v_mov_b32_e32 v36, v22
	v_mov_b32_e32 v37, v22
	s_waitcnt lgkmcnt(0)
	s_barrier
	v_and_b32_e32 v2, 63, v0
	v_lshlrev_b32_e32 v2, 2, v2
	v_add_u32_e32 v3, s0, v2
	ds_read_b32 v238, v3 offset:17920
	ds_read_b32 v240, v2 offset:18176
	v_add_u32_e32 v3, s28, v2
	ds_read_b32 v254, v3 offset:17920
	s_waitcnt lgkmcnt(0)
	v_and_b32_e32 v2, 7, v0
	v_bfe_u32 v3, v0, 4, 2
	v_xor_b32_e32 v66, v3, v2
	v_or_b32_e32 v3, 4, v3
	v_xor_b32_e32 v3, v3, v2
	v_lshlrev_b32_e32 v66, 4, v66
	v_lshlrev_b32_e32 v3, 4, v3
	v_lshl_add_u32 v2, v150, 7, v66
	v_lshl_add_u32 v3, v150, 7, v3
	ds_read_b128 v[154:157], v2
	ds_read_b128 v[158:161], v2 offset:8192
	ds_read_b128 v[162:165], v3
	ds_read_b128 v[166:169], v3 offset:8192
	ds_read_b128 v[172:175], v2 offset:2048
	ds_read_b128 v[176:179], v2 offset:10240
	ds_read_b128 v[180:183], v3 offset:2048
	ds_read_b128 v[184:187], v3 offset:10240
	s_waitcnt lgkmcnt(0)
	s_and_b64 vcc, exec, s[4:5]
	s_cbranch_vccz .La0_setup_done
	v_add_u32_e32 v66, s69, v252
	v_lshrrev_b32_e32 v67, 3, v66
	v_and_b32_e32 v68, 7, v66
	v_lshlrev_b32_e32 v69, 5, v68
	v_lshlrev_b32_e32 v68, 4, v68
	v_mov_b32_e32 v70, 0x16540
	v_add_u32_e32 v71, 0, v67
	v_sub_u32_e32 v72, 65, v71
	v_cndmask_b32_e64 v71, v71, v72, s[16:17]
	v_mul_u32_u24_e32 v71, 0x110, v71
	v_add_u32_e32 v71, v71, v69
	v_add_u32_e32 v22, 0x5800, v71
	v_add_u32_e32 v71, 32, v67
	v_sub_u32_e32 v72, 65, v71
	v_cndmask_b32_e64 v71, v71, v72, s[16:17]
	v_mul_u32_u24_e32 v71, 0x110, v71
	v_add_u32_e32 v71, v71, v69
	v_add_u32_e32 v23, 0x5800, v71
	v_add_u32_e32 v71, 64, v67
	v_sub_u32_e32 v72, 65, v71
	v_cndmask_b32_e64 v71, v71, v72, s[16:17]
	v_mul_u32_u24_e32 v71, 0x110, v71
	v_add_u32_e32 v71, v71, v69
	v_add_u32_e32 v73, 0x5800, v71
	v_subrev_u32_e32 v71, 2, v67
	v_sub_u32_e32 v72, 65, v71
	v_cndmask_b32_e64 v71, v71, v72, s[16:17]
	v_mul_u32_u24_e32 v71, 0x110, v71
	v_add_u32_e32 v71, v71, v69
	v_add_u32_e32 v24, 0x9e20, v71
	v_cmp_gt_u32_e32 vcc, 16, v66
	s_nop 1
	v_cndmask_b32_e32 v24, v24, v73, vcc
	v_add_u32_e32 v71, 30, v67
	v_sub_u32_e32 v72, 65, v71
	v_cndmask_b32_e64 v71, v71, v72, s[16:17]
	v_mul_u32_u24_e32 v71, 0x110, v71
	v_add_u32_e32 v71, v71, v69
	v_add_u32_e32 v25, 0x9e20, v71
	v_add_u32_e32 v71, 62, v67
	v_sub_u32_e32 v72, 65, v71
	v_cndmask_b32_e64 v71, v71, v72, s[16:17]
	v_mul_u32_u24_e32 v71, 0x110, v71
	v_add_u32_e32 v71, v71, v69
	v_add_u32_e32 v26, 0x9e20, v71
	v_subrev_u32_e32 v71, 4, v67
	v_sub_u32_e32 v72, 65, v71
	v_cndmask_b32_e64 v71, v71, v72, s[16:17]
	v_mul_u32_u24_e32 v71, 0x80, v71
	v_add_u32_e32 v71, v71, v68
	v_add_u32_e32 v27, 0xe440, v71
	v_cmp_gt_u32_e32 vcc, 32, v66
	s_nop 1
	v_cndmask_b32_e32 v26, v70, v26, vcc
	v_cndmask_b32_e32 v27, v27, v70, vcc
	v_add_u32_e32 v71, 28, v67
	v_sub_u32_e32 v72, 65, v71
	v_cndmask_b32_e64 v71, v71, v72, s[16:17]
	v_mul_u32_u24_e32 v71, 0x80, v71
	v_add_u32_e32 v71, v71, v68
	v_add_u32_e32 v28, 0xe440, v71
	v_add_u32_e32 v71, 60, v67
	v_sub_u32_e32 v72, 65, v71
	v_cndmask_b32_e64 v71, v71, v72, s[16:17]
	v_mul_u32_u24_e32 v71, 0x80, v71
	v_add_u32_e32 v71, v71, v68
	v_add_u32_e32 v29, 0xe440, v71
	v_cmp_gt_u32_e32 vcc, 48, v66
	s_nop 1
	v_cndmask_b32_e32 v29, v70, v29, vcc
	v_lshlrev_b32_e32 v71, 2, v252
	v_add_u32_e32 v71, 0x4f00, v71
	v_cndmask_b32_e64 v30, v70, v71, s[8:9]
.La0_setup_done:
	v_and_b32_e32 v2, 15, v0
	v_add_u32_e32 v2, s80, v2
	v_sub_u32_e32 v3, 63, v2
	v_cndmask_b32_e64 v2, v2, v3, s[16:17]
	v_lshlrev_b32_e32 v2, 7, v2
	v_and_b32_e32 v3, 48, v0
	v_add_u32_e32 v189, v2, v3
	v_lshrrev_b32_e32 v2, 3, v0
	v_sub_u32_e32 v3, 63, v2
	v_cndmask_b32_e64 v2, v2, v3, s[16:17]
	v_and_b32_e32 v3, 7, v0
	v_lshlrev_b32_e32 v3, 4, v3
	v_lshl_add_u32 v3, v2, 10, v3
	s_lshl_b32 s98, s1, 1
	v_add_u32_e32 v3, s98, v3
	s_lshl_b32 s98, s50, 10
	s_add_u32 s98, s98, 0x12800000
	v_add_u32_e32 v191, s98, v3
	s_lshl_b32 s98, s66, 10
	s_add_u32 s98, s98, 0x10800000
	v_add_u32_e32 v192, s98, v3
	s_lshl_b32 s98, s50, 5
	s_add_u32 s98, s98, s27
	v_lshl_add_u32 v193, v2, 5, s98
	s_branch .LBB0_541

.LBB0_552:
	s_lshl_b32 s30, s51, 6
	s_sub_i32 s22, 0x800, s30
	s_sub_i32 s2, s30, 64
	v_mov_b32_e32 v90, v0
	s_cmp_lt_u32 s51, 17
	s_cbranch_scc1 .Lscan_skip_pload
	s_and_b64 s[18:19], s[16:17], exec
	s_cselect_b32 s18, s22, s2
	s_lshl_b32 s98, s18, 10
	s_lshl_b32 s99, s18, 5
	buffer_load_dwordx4 v[70:73], v191, s[60:63], s98 offen sc1
	buffer_load_dwordx4 v[66:69], v192, s[60:63], s98 offen
	buffer_load_dword v213, v193, s[60:63], s99 offen sc1
.Lscan_skip_pload:
	s_bitcmp0_b32 s51, 0
	ds_read_u16 v75, v234 offset:58688
	ds_read_u16 v79, v234 offset:59072
	ds_read_u16 v86, v234 offset:59200
	ds_read_u16 v87, v234 offset:59328
	ds_read_u16 v77, v234 offset:58944
	ds_read_u16 v80, v234 offset:58816
	ds_read_u16 v82, v234 offset:58432
	ds_read_u16 v83, v234 offset:58560
	s_waitcnt lgkmcnt(7)
	v_lshlrev_b32_e32 v76, 16, v75
	ds_read_u16 v75, v234 offset:59456
	ds_read_u16 v3, v234 offset:59584
	s_waitcnt lgkmcnt(5)
	v_lshlrev_b32_e32 v78, 16, v77
	s_waitcnt lgkmcnt(4)
	v_lshlrev_b32_e32 v77, 16, v80
	s_waitcnt lgkmcnt(2)
	v_lshlrev_b32_e32 v83, 16, v83
	v_lshlrev_b32_e32 v82, 16, v82
	v_pk_mov_b32 v[84:85], v[82:83], v[76:77] op_sel:[1,0]
	v_mov_b32_e32 v80, v77
	v_mov_b32_e32 v81, v78
	v_pk_mul_f32 v[84:85], v[240:241], v[84:85] op_sel_hi:[0, 1]
	s_waitcnt lgkmcnt(0)
	v_pk_fma_f32 v[82:83], v[238:239], v[82:83], v[84:85] op_sel_hi:[0, 1, 1]
	v_pk_mul_f32 v[80:81], v[240:241], v[80:81] op_sel_hi:[0, 1]
	v_lshlrev_b32_e32 v79, 16, v79
	v_pk_fma_f32 v[82:83], v[254:255], v[76:77], v[82:83] op_sel_hi:[0, 1, 1]
	v_pk_fma_f32 v[76:77], v[238:239], v[76:77], v[80:81] op_sel_hi:[0, 1, 1]
	v_lshlrev_b32_e32 v80, 16, v86
	v_lshlrev_b32_e32 v81, 16, v87
	v_lshlrev_b32_e32 v87, 16, v75
	v_mov_b32_e32 v86, v81
	v_pk_mov_b32 v[88:89], v[78:79], v[80:81] op_sel:[1,0]
	v_mov_b32_e32 v84, v87
	v_pk_mul_f32 v[88:89], v[240:241], v[88:89] op_sel_hi:[0, 1]
	v_pk_mul_f32 v[86:87], v[240:241], v[86:87] op_sel_hi:[0, 1]
	s_cselect_b32 s18, s35, 0x22540
	s_cmp_lg_u32 s51, 31
	v_pk_fma_f32 v[76:77], v[254:255], v[78:79], v[76:77] op_sel_hi:[0, 1, 1]
	v_lshlrev_b32_e32 v85, 16, v3
	v_pk_fma_f32 v[78:79], v[238:239], v[78:79], v[88:89] op_sel_hi:[0, 1, 1]
	v_pk_fma_f32 v[2:3], v[238:239], v[80:81], v[86:87] op_sel_hi:[0, 1, 1]
	s_cselect_b64 s[48:49], -1, 0
	s_add_i32 s31, s18, 0
	v_pk_fma_f32 v[78:79], v[254:255], v[80:81], v[78:79] op_sel_hi:[0, 1, 1]
	v_pk_fma_f32 v[2:3], v[254:255], v[84:85], v[2:3] op_sel_hi:[0, 1, 1]
	v_cvt_pk_bf16_f32 v75, v76, v77
	v_cvt_pk_bf16_f32 v74, v82, v83
	v_add_u32_e32 v80, s31, v235
	ds_write_b64 v80, v[74:75]
	v_cvt_pk_bf16_f32 v75, v2, v3
	v_cvt_pk_bf16_f32 v74, v78, v79
	v_add_u32_e32 v2, s31, v236
	ds_write_b64 v2, v[74:75]
	v_add_u32_e32 v2, 0x5800, v151
	ds_read2_b32 v[104:105], v2 offset1:16
	ds_read2_b32 v[118:119], v2 offset0:68 offset1:136
	v_add_u32_e32 v2, 0x9c00, v151
	ds_read2_b32 v[106:107], v2 offset0:136 offset1:152
	v_add_u32_e32 v2, 0x9e00, v151
	ds_read2_b32 v[120:121], v2 offset0:76 offset1:144
	v_add_u32_e32 v2, 0x5a00, v151
	ds_read2_b32 v[128:129], v2 offset0:76 offset1:144
	v_add_u32_e32 v2, 0xa000, v151
	v_add_u32_e32 v4, 0x4000, v152
	ds_read2_b32 v[126:127], v2 offset0:84 offset1:152
	ds_read_b128 v[74:77], v148 offset:20224
	ds_read_b32 v219, v151 offset:23888
	ds_read_b32 v3, v153 offset:41840
	ds_read_b32 v221, v151 offset:41840
	v_add_u32_e32 v2, 0x4000, v210
	ds_read2_b32 v[94:95], v4 offset0:64 offset1:80
	v_add_u32_e32 v4, 0x4000, v211
	ds_read2_b32 v[90:91], v2 offset1:16
	ds_read2_b32 v[92:93], v4 offset1:16
	ds_read2_b32 v[86:87], v2 offset0:192 offset1:208
	ds_read_b32 v99, v153 offset:23888
	s_waitcnt vmcnt(11)
	v_mfma_f32_16x16x32_bf16 v[78:81], v[10:13], v[154:157], 0
	v_add_u32_e32 v2, 0x4400, v152
	ds_read2_b32 v[102:103], v2 offset1:16
	ds_read2_b32 v[100:101], v4 offset0:192 offset1:208
	v_add_u32_e32 v2, 0x4800, v152
	s_waitcnt vmcnt(10)
	v_mfma_f32_16x16x32_bf16 v[136:139], v[6:9], v[162:165], v[78:81]
	ds_read2_b32 v[96:97], v2 offset0:128 offset1:144
	ds_read2_b32 v[88:89], v2 offset0:192 offset1:208
	s_nop 0
	v_add_u32_e32 v2, 0x4c00, v152
	ds_read2_b32 v[132:133], v2 offset0:64 offset1:80
	s_waitcnt vmcnt(9)
	v_mfma_f32_16x16x32_bf16 v[82:85], v[18:21], v[158:161], 0
	s_add_i32 s81, s30, 64
	s_sub_i32 s2, 0x780, s30
	s_cmp_eq_u32 s51, 31
	s_waitcnt vmcnt(8)
	v_mfma_f32_16x16x32_bf16 v[214:217], v[14:17], v[166:169], v[82:85]
	ds_read2_b32 v[116:117], v2 offset0:128 offset1:144
	s_nop 0
	v_add_u32_e32 v2, 0x5800, v153
	ds_read2_b32 v[112:113], v2 offset0:68 offset1:136
	v_mfma_f32_16x16x32_bf16 v[10:13], v[10:13], v[172:175], 0
	v_add_u32_e32 v2, 0x9e00, v153
	ds_read2_b32 v[108:109], v2 offset0:76 offset1:144
	v_add_u32_e32 v2, 0x5a00, v153
	v_mfma_f32_16x16x32_bf16 v[82:85], v[6:9], v[180:183], v[10:13]
	s_cselect_b32 s23, 0x7c0, s81
	ds_read2_b32 v[114:115], v2 offset0:76 offset1:144
	v_mfma_f32_16x16x32_bf16 v[10:13], v[18:21], v[176:179], 0
	v_add_u32_e32 v2, 0xa000, v153
	s_cselect_b32 s24, 31, s2
	s_and_b64 s[18:19], s[16:17], exec
	ds_read2_b32 v[110:111], v2 offset0:84 offset1:152
	s_cselect_b32 s18, s24, s23
	s_andn2_b32 s98, s18, 63
	s_add_i32 s98, s98, s66
	s_lshl_b32 s98, s98, 7
	s_add_u32 s98, s98, 0x1a800000
	s_add_u32 s99, s98, 0x400000
	v_mfma_f32_16x16x32_bf16 v[78:81], v[14:17], v[184:187], v[10:13]
	s_waitcnt lgkmcnt(5)
	v_pk_add_f32 v[6:7], v[132:133], v[136:137] op_sel_hi:[0,1]
	v_exp_f32_e32 v6, v6
	v_exp_f32_e32 v7, v7
	v_pk_add_f32 v[10:11], v[132:133], v[138:139] op_sel_hi:[0,1]
	v_exp_f32_e32 v10, v10
	v_exp_f32_e32 v11, v11
	v_pk_add_f32 v[6:7], v[6:7], 1.0 op_sel_hi:[1,0]
	v_rcp_f32_e32 v16, v6
	v_rcp_f32_e32 v17, v7
	v_pk_add_f32 v[6:7], v[10:11], 1.0 op_sel_hi:[1,0]
	s_waitcnt lgkmcnt(4)
	v_pk_add_f32 v[214:215], v[116:117], v[214:215] op_sel_hi:[0,1]
	v_rcp_f32_e32 v18, v6
	v_rcp_f32_e32 v19, v7
	v_pk_mul_f32 v[222:223], v[16:17], s[70:71] op_sel_hi:[1,0]
	buffer_load_dwordx4 v[10:13], v189, s[60:63], s98 offen
	buffer_load_dwordx4 v[6:9], v189, s[60:63], s98 offen offset:64
	v_pk_fma_f32 v[224:225], v[16:17], s[70:71], v[222:223] op_sel:[0,0,1] op_sel_hi:[1,0,0]
	v_mul_f32_e32 v2, 0xbf60028a, v19
	v_pk_fma_f32 v[226:227], v[18:19], s[70:71], v[224:225] op_sel_hi:[1,0,1]
	buffer_load_dwordx4 v[18:21], v189, s[60:63], s99 offen
	buffer_load_dwordx4 v[14:17], v189, s[60:63], s99 offen offset:64
	v_pk_add_f32 v[228:229], v[2:3], v[226:227] op_sel_hi:[0,1]
	v_mov_b32_e32 v136, v228
	v_mov_b32_e32 v138, v228
	s_nop 1
	v_permlane16_swap_b32_e32 v136, v138
	v_mov_b32_e32 v137, v136
	v_mov_b32_e32 v139, v138
	s_nop 1
	v_permlane32_swap_b32_e32 v136, v137
	v_permlane32_swap_b32_e32 v138, v139
	v_exp_f32_e32 v214, v214
	v_exp_f32_e32 v215, v215
	v_pk_add_f32 v[216:217], v[116:117], v[216:217] op_sel_hi:[0,1]
	v_exp_f32_e32 v216, v216
	v_exp_f32_e32 v217, v217
	v_cndmask_b32_e64 v2, v136, 0, s[10:11]
	v_cndmask_b32_e64 v4, 0, v138, s[12:13]
	v_pk_add_f32 v[214:215], v[214:215], 1.0 op_sel_hi:[1,0]
	v_add_f32_e32 v2, v2, v4
	v_cndmask_b32_e64 v4, 0, v137, s[14:15]
	v_rcp_f32_e32 v214, v214
	v_rcp_f32_e32 v215, v215
	v_add_f32_e32 v2, v2, v4
	v_mov_b32_e32 v223, v224
	v_pk_add_f32 v[216:217], v[216:217], 1.0 op_sel_hi:[1,0]
	v_mov_b32_e32 v122, v106
	v_mov_b32_e32 v123, v120
	v_mov_b32_e32 v130, v121
	v_pk_add_f32 v[224:225], v[222:223], v[2:3] op_sel_hi:[1,0]
	v_mov_b32_e32 v227, v228
	v_rcp_f32_e32 v216, v216
	v_rcp_f32_e32 v217, v217
	v_pk_mul_f32 v[120:121], v[120:121], v[102:103] op_sel_hi:[1,0]
	v_mov_b32_e32 v131, v126
	v_pk_add_f32 v[226:227], v[226:227], v[2:3] op_sel_hi:[1,0]
	v_exp_f32_e32 v228, v224
	v_sub_f32_e32 v2, v224, v222
	v_pk_fma_f32 v[120:121], v[122:123], v[86:87], v[120:121] op_sel_hi:[1,0,1]
	v_pk_mul_f32 v[122:123], v[126:127], v[102:103] op_sel_hi:[1,0]
	v_exp_f32_e32 v222, v2
	v_pk_fma_f32 v[120:121], v[130:131], v[100:101], v[120:121] op_sel_hi:[1,0,1]
	v_pk_fma_f32 v[122:123], v[130:131], v[86:87], v[122:123] op_sel_hi:[1,0,1]
	v_pk_add_f32 v[130:131], v[214:215], -1.0 op_sel_hi:[1,0]
	v_exp_f32_e32 v229, v225
	v_exp_f32_e32 v230, v226
	v_exp_f32_e64 v232, -v224
	v_exp_f32_e64 v233, -v225
	v_pk_mul_f32 v[130:131], v[88:89], v[130:131] op_sel_hi:[0,1]
	v_mov_b32_e32 v220, v127
	v_pk_mul_f32 v[126:127], v[96:97], v[120:121] op_sel_hi:[0,1]
	v_pk_fma_f32 v[120:121], v[120:121], v[130:131], v[120:121]
	v_pk_add_f32 v[130:131], v[216:217], -1.0 op_sel_hi:[1,0]
	v_mov_b32_e32 v124, v104
	v_mov_b32_e32 v125, v118
	v_mov_b32_e32 v134, v119
	v_exp_f32_e32 v231, v227
	v_exp_f32_e64 v226, -v226
	v_exp_f32_e64 v227, -v227
	v_mov_b32_e32 v223, v228
	v_pk_mul_f32 v[118:119], v[118:119], v[94:95] op_sel_hi:[1,0]
	v_pk_fma_f32 v[122:123], v[220:221], v[100:101], v[122:123] op_sel_hi:[1,0,1]
	v_pk_mul_f32 v[126:127], v[74:75], v[126:127]
	v_pk_mul_f32 v[130:131], v[88:89], v[130:131] op_sel_hi:[0,1]
	v_mov_b32_e32 v135, v128
	v_mov_b32_e32 v218, v129
	v_pk_fma_f32 v[118:119], v[124:125], v[90:91], v[118:119] op_sel_hi:[1,0,1]
	v_pk_mul_f32 v[124:125], v[128:129], v[94:95] op_sel_hi:[1,0]
	v_pk_mul_f32 v[128:129], v[96:97], v[122:123] op_sel_hi:[0,1]
	v_pk_fma_f32 v[122:123], v[122:123], v[130:131], v[122:123]
	v_pk_mul_f32 v[130:131], v[126:127], v[222:223] neg_lo:[0,1] neg_hi:[0,1]
	v_pk_mul_f32 v[126:127], v[126:127], v[214:215]
	v_mov_b32_e32 v224, v229
	v_mov_b32_e32 v225, v230
	v_pk_fma_f32 v[118:119], v[134:135], v[92:93], v[118:119] op_sel_hi:[1,0,1]
	v_pk_mul_f32 v[128:129], v[76:77], v[128:129]
	v_pk_mul_f32 v[126:127], v[126:127], v[232:233]
	v_pk_fma_f32 v[124:125], v[134:135], v[90:91], v[124:125] op_sel_hi:[1,0,1]
	v_pk_mul_f32 v[134:135], v[128:129], v[224:225] neg_lo:[0,1] neg_hi:[0,1]
	v_pk_mul_f32 v[128:129], v[128:129], v[216:217]
	v_pk_mul_f32 v[120:121], v[120:121], v[232:233]
	v_pk_mul_f32 v[118:119], v[118:119], v[228:229]
	v_pk_fma_f32 v[124:125], v[218:219], v[92:93], v[124:125] op_sel_hi:[1,0,1]
	v_pk_mul_f32 v[128:129], v[128:129], v[226:227]
	v_pk_mul_f32 v[122:123], v[122:123], v[226:227]
	v_pk_mul_f32 v[124:125], v[124:125], v[230:231]
	v_cvt_pk_bf16_f32 v125, v124, v125
	v_cvt_pk_bf16_f32 v124, v118, v119
	v_cvt_pk_bf16_f32 v118, v126, v127
	v_cvt_pk_bf16_f32 v119, v128, v129
	v_cvt_pk_bf16_f32 v120, v120, v121
	v_cvt_pk_bf16_f32 v121, v122, v123
	v_cvt_pk_bf16_f32 v122, v130, v131
	v_cvt_pk_bf16_f32 v123, v134, v135
	v_add_u32_e32 v2, v149, v170
	ds_write_b128 v2, v[118:121] offset:32768
	ds_write_b128 v2, v[122:125]
	s_and_saveexec_b64 s[18:19], s[10:11]
	s_cbranch_execz .LBB0_554
	s_waitcnt lgkmcnt(2)
	v_pk_add_f32 v[118:119], v[138:139], v[136:137]
	s_nop 0
	v_add_f32_e32 v2, v118, v119
	v_exp_f32_e32 v2, v2
	ds_write_b32 v171, v2 offset:20992
.LBB0_554:
	s_or_b64 exec, exec, s[18:19]
	s_waitcnt lgkmcnt(2)
	v_mov_b32_e32 v2, v133
	v_pk_add_f32 v[82:83], v[2:3], v[82:83] op_sel_hi:[0,1]
	v_exp_f32_e32 v82, v82
	v_exp_f32_e32 v83, v83
	v_pk_add_f32 v[84:85], v[2:3], v[84:85] op_sel_hi:[0,1]
	v_exp_f32_e32 v84, v84
	v_exp_f32_e32 v85, v85
	v_pk_add_f32 v[82:83], v[82:83], 1.0 op_sel_hi:[1,0]
	v_rcp_f32_e32 v82, v82
	v_rcp_f32_e32 v83, v83
	v_pk_add_f32 v[84:85], v[84:85], 1.0 op_sel_hi:[1,0]
	v_rcp_f32_e32 v84, v84
	v_rcp_f32_e32 v85, v85
	v_pk_mul_f32 v[122:123], v[82:83], s[70:71] op_sel_hi:[1,0]
	v_pk_fma_f32 v[124:125], v[82:83], s[70:71], v[122:123] op_sel:[0,0,1] op_sel_hi:[1,0,0]
	v_mul_f32_e32 v2, 0xbf60028a, v85
	v_pk_fma_f32 v[126:127], v[84:85], s[70:71], v[124:125] op_sel_hi:[1,0,1]
	v_mov_b32_e32 v123, v124
	v_pk_add_f32 v[128:129], v[2:3], v[126:127] op_sel_hi:[0,1]
	v_mov_b32_e32 v82, v128
	v_mov_b32_e32 v84, v128
	s_nop 1
	v_permlane16_swap_b32_e32 v82, v84
	v_mov_b32_e32 v83, v82
	v_mov_b32_e32 v85, v84
	s_nop 1
	v_permlane32_swap_b32_e32 v82, v83
	v_permlane32_swap_b32_e32 v84, v85
	v_mov_b32_e32 v127, v128
	v_mov_b32_e32 v104, v105
	v_cndmask_b32_e64 v4, v82, 0, s[10:11]
	v_cndmask_b32_e64 v86, 0, v84, s[12:13]
	v_add_f32_e32 v4, v4, v86
	v_cndmask_b32_e64 v86, 0, v83, s[14:15]
	v_add_f32_e32 v4, v4, v86
	v_pk_add_f32 v[124:125], v[122:123], v[4:5] op_sel_hi:[1,0]
	v_pk_add_f32 v[126:127], v[126:127], v[4:5] op_sel_hi:[1,0]
	v_sub_f32_e32 v4, v124, v122
	v_exp_f32_e32 v122, v4
	v_mov_b32_e32 v4, v117
	v_pk_add_f32 v[80:81], v[4:5], v[80:81] op_sel_hi:[0,1]
	v_pk_add_f32 v[78:79], v[4:5], v[78:79] op_sel_hi:[0,1]
	v_exp_f32_e32 v80, v80
	v_exp_f32_e32 v81, v81
	v_exp_f32_e32 v78, v78
	v_exp_f32_e32 v79, v79
	v_mov_b32_e32 v86, v95
	v_mov_b32_e32 v105, v112
	v_mov_b32_e32 v118, v113
	v_mov_b32_e32 v119, v114
	v_pk_add_f32 v[80:81], v[80:81], 1.0 op_sel_hi:[1,0]
	v_mov_b32_e32 v4, v91
	v_pk_mul_f32 v[90:91], v[112:113], v[86:87] op_sel_hi:[1,0]
	v_mov_b32_e32 v88, v93
	v_pk_mul_f32 v[92:93], v[114:115], v[86:87] op_sel_hi:[1,0]
	v_mov_b32_e32 v86, v103
	v_mov_b32_e32 v106, v107
	v_mov_b32_e32 v107, v108
	v_mov_b32_e32 v98, v115
	v_pk_add_f32 v[78:79], v[78:79], 1.0 op_sel_hi:[1,0]
	v_rcp_f32_e32 v80, v80
	v_rcp_f32_e32 v81, v81
	v_pk_fma_f32 v[90:91], v[104:105], v[4:5], v[90:91] op_sel_hi:[1,0,1]
	v_pk_fma_f32 v[92:93], v[118:119], v[4:5], v[92:93] op_sel_hi:[1,0,1]
	v_mov_b32_e32 v4, v87
	v_pk_mul_f32 v[94:95], v[108:109], v[86:87] op_sel_hi:[1,0]
	v_mov_b32_e32 v120, v109
	v_mov_b32_e32 v121, v110
	v_exp_f32_e32 v128, v124
	v_rcp_f32_e32 v78, v78
	v_rcp_f32_e32 v79, v79
	v_pk_fma_f32 v[90:91], v[118:119], v[88:89], v[90:91] op_sel_hi:[1,0,1]
	v_pk_fma_f32 v[92:93], v[98:99], v[88:89], v[92:93] op_sel_hi:[1,0,1]
	v_pk_fma_f32 v[94:95], v[106:107], v[4:5], v[94:95] op_sel_hi:[1,0,1]
	v_mov_b32_e32 v88, v101
	v_pk_mul_f32 v[86:87], v[110:111], v[86:87] op_sel_hi:[1,0]
	v_mov_b32_e32 v2, v111
	v_pk_fma_f32 v[94:95], v[120:121], v[88:89], v[94:95] op_sel_hi:[1,0,1]
	v_pk_fma_f32 v[86:87], v[120:121], v[4:5], v[86:87] op_sel_hi:[1,0,1]
	v_mov_b32_e32 v4, v97
	v_exp_f32_e32 v129, v125
	v_exp_f32_e32 v130, v126
	v_exp_f32_e64 v132, -v124
	v_exp_f32_e64 v133, -v125
	v_pk_fma_f32 v[2:3], v[2:3], v[88:89], v[86:87] op_sel_hi:[1,0,1]
	v_pk_mul_f32 v[86:87], v[4:5], v[94:95] op_sel_hi:[0,1]
	v_pk_mul_f32 v[74:75], v[74:75], v[86:87]
	v_pk_mul_f32 v[86:87], v[4:5], v[2:3] op_sel_hi:[0,1]
	v_mov_b32_e32 v4, v89
	v_pk_add_f32 v[88:89], v[80:81], -1.0 op_sel_hi:[1,0]
	v_exp_f32_e32 v131, v127
	v_exp_f32_e64 v126, -v126
	v_exp_f32_e64 v127, -v127
	v_mov_b32_e32 v123, v128
	v_pk_mul_f32 v[76:77], v[76:77], v[86:87]
	v_pk_add_f32 v[86:87], v[78:79], -1.0 op_sel_hi:[1,0]
	v_pk_mul_f32 v[88:89], v[4:5], v[88:89] op_sel_hi:[0,1]
	v_pk_mul_f32 v[86:87], v[4:5], v[86:87] op_sel_hi:[0,1]
	v_pk_fma_f32 v[2:3], v[2:3], v[88:89], v[2:3]
	v_pk_mul_f32 v[88:89], v[74:75], v[122:123] neg_lo:[0,1] neg_hi:[0,1]
	v_pk_mul_f32 v[74:75], v[74:75], v[78:79]
	v_mov_b32_e32 v124, v129
	v_mov_b32_e32 v125, v130
	v_pk_fma_f32 v[86:87], v[94:95], v[86:87], v[94:95]
	v_pk_mul_f32 v[74:75], v[74:75], v[132:133]
	v_pk_mul_f32 v[94:95], v[76:77], v[124:125] neg_lo:[0,1] neg_hi:[0,1]
	v_pk_mul_f32 v[76:77], v[76:77], v[80:81]
	v_pk_mul_f32 v[78:79], v[86:87], v[132:133]
	v_pk_mul_f32 v[80:81], v[90:91], v[128:129]
	v_pk_mul_f32 v[76:77], v[76:77], v[126:127]
	v_pk_mul_f32 v[2:3], v[2:3], v[126:127]
	v_pk_mul_f32 v[86:87], v[92:93], v[130:131]
	v_cvt_pk_bf16_f32 v74, v74, v75
	v_cvt_pk_bf16_f32 v75, v76, v77
	v_cvt_pk_bf16_f32 v76, v78, v79
	v_cvt_pk_bf16_f32 v77, v2, v3
	v_cvt_pk_bf16_f32 v78, v88, v89
	v_cvt_pk_bf16_f32 v79, v94, v95
	v_cvt_pk_bf16_f32 v80, v80, v81
	v_cvt_pk_bf16_f32 v81, v86, v87
	ds_write_b128 v194, v[74:77] offset:32768
	ds_write_b128 v194, v[78:81]
	s_and_saveexec_b64 s[18:19], s[10:11]
	s_cbranch_execz .LBB0_556
	s_waitcnt lgkmcnt(2)
	v_pk_add_f32 v[2:3], v[84:85], v[82:83]
	s_nop 0
	v_add_f32_e32 v2, v2, v3
	v_exp_f32_e32 v2, v2
	ds_write_b32 v171, v2 offset:21056

	.amdhsa_kernel _Z7hyb_fwd4Args
		.amdhsa_group_segment_fixed_size 0
		.amdhsa_private_segment_fixed_size 0
		.amdhsa_kernarg_size 448
		.amdhsa_user_sgpr_count 2
		.amdhsa_user_sgpr_dispatch_ptr 0
		.amdhsa_user_sgpr_queue_ptr 0
		.amdhsa_user_sgpr_kernarg_segment_ptr 1
		.amdhsa_user_sgpr_dispatch_id 0
		.amdhsa_user_sgpr_kernarg_preload_length 0
		.amdhsa_user_sgpr_kernarg_preload_offset 0
		.amdhsa_user_sgpr_private_segment_size 0
		.amdhsa_uses_dynamic_stack 0
		.amdhsa_enable_private_segment 0
		.amdhsa_system_sgpr_workgroup_id_x 1
		.amdhsa_system_sgpr_workgroup_id_y 0
		.amdhsa_system_sgpr_workgroup_id_z 0
		.amdhsa_system_sgpr_workgroup_info 0
		.amdhsa_system_vgpr_workitem_id 0
		.amdhsa_next_free_vgpr 256
		.amdhsa_next_free_sgpr 100
		.amdhsa_accum_offset 256
		.amdhsa_reserve_vcc 1
		.amdhsa_float_round_mode_32 0
		.amdhsa_float_round_mode_16_64 0
		.amdhsa_float_denorm_mode_32 3
		.amdhsa_float_denorm_mode_16_64 3
		.amdhsa_dx10_clamp 1
		.amdhsa_ieee_mode 1
		.amdhsa_fp16_overflow 0
		.amdhsa_tg_split 0
		.amdhsa_exception_fp_ieee_invalid_op 0
		.amdhsa_exception_fp_denorm_src 0
		.amdhsa_exception_fp_ieee_div_zero 0
		.amdhsa_exception_fp_ieee_overflow 0
		.amdhsa_exception_fp_ieee_underflow 0
		.amdhsa_exception_fp_ieee_inexact 0
		.amdhsa_exception_int_div_zero 0
	.end_amdhsa_kernel

amdhsa.kernels:
  - .agpr_count:     0
    .args:
      - .offset:         0
        .size:           192
        .value_kind:     by_value
      - .offset:         192
        .size:           4
        .value_kind:     hidden_block_count_x
      - .offset:         196
        .size:           4
        .value_kind:     hidden_block_count_y
      - .offset:         200
        .size:           4
        .value_kind:     hidden_block_count_z
      - .offset:         204
        .size:           2
        .value_kind:     hidden_group_size_x
      - .offset:         206
        .size:           2
        .value_kind:     hidden_group_size_y
      - .offset:         208
        .size:           2
        .value_kind:     hidden_group_size_z
      - .offset:         210
        .size:           2
        .value_kind:     hidden_remainder_x
      - .offset:         212
        .size:           2
        .value_kind:     hidden_remainder_y
      - .offset:         214
        .size:           2
        .value_kind:     hidden_remainder_z
      - .offset:         232
        .size:           8
        .value_kind:     hidden_global_offset_x
      - .offset:         240
        .size:           8
        .value_kind:     hidden_global_offset_y
      - .offset:         248
        .size:           8
        .value_kind:     hidden_global_offset_z
      - .offset:         256
        .size:           2
        .value_kind:     hidden_grid_dims
      - .offset:         312
        .size:           4
        .value_kind:     hidden_dynamic_lds_size
    .group_segment_fixed_size: 0
    .kernarg_segment_align: 8
    .kernarg_segment_size: 448
    .language:       OpenCL C
    .language_version:
      - 2
      - 0
    .max_flat_workgroup_size: 512
    .name:           _Z7hyb_fwd4Args
    .private_segment_fixed_size: 0
    .sgpr_count:     106
    .sgpr_spill_count: 16
    .symbol:         _Z7hyb_fwd4Args.kd
    .uniform_work_group_size: 1
    .uses_dynamic_stack: false
    .vgpr_count:     256
    .vgpr_spill_count: 0
    .wavefront_size: 64
